# weight conversion routine processes two items per iteration (16 loads in flight per wave instead of 8)
# baseline (speedup 1.0000x reference)
.Lcvth_loop:
	s_cmp_ge_u32 s0, s14
	s_cbranch_scc1 .Lcvth_done2
	s_mov_b32 s23, 0
.Lcvth_dec:
	s_cmp_lt_u32 s0, 2816
	s_cbranch_scc1 .Lcvth_job0
	s_cmp_lt_u32 s0, 4224
	s_cbranch_scc1 .Lcvth_job1
	s_cmp_lt_u32 s0, 4992
	s_cbranch_scc1 .Lcvth_job2
	s_cmp_lt_u32 s0, 5248
	s_cbranch_scc1 .Lcvth_job3
	s_cmp_lt_u32 s0, 5504
	s_cbranch_scc1 .Lcvth_job4
	s_cmp_lt_u32 s0, 6528
	s_cbranch_scc1 .Lcvth_job5
	s_cmp_lt_u32 s0, 7552
	s_cbranch_scc1 .Lcvth_job6
	s_cmp_lt_u32 s0, 8576
	s_cbranch_scc1 .Lcvth_job7
	s_cmp_lt_u32 s0, 9088
	s_cbranch_scc1 .Lcvth_job8
	s_cmp_lt_u32 s0, 9600
	s_cbranch_scc1 .Lcvth_job9
	s_cmp_lt_u32 s0, 10112
	s_cbranch_scc1 .Lcvth_job10
	s_cmp_lt_u32 s0, 12928
	s_cbranch_scc1 .Lcvth_job11
	s_branch .Lcvth_job12

.Lcvth_ud:
	s_mul_i32 s11, s11, s9
	s_add_u32 s6, s6, s11
	s_addc_u32 s7, s7, 0
	s_cmp_lg_u32 s23, 0
	s_cbranch_scc1 .Lcvth_ldB
	v_mad_u32_u24 v0, v100, s8, v105
	s_lshl_b32 s13, s8, 3
	global_load_dwordx4 v[8:11], v0, s[4:5]
	s_add_u32 s4, s4, s13
	s_addc_u32 s5, s5, 0
	s_nop 0
	global_load_dwordx4 v[12:15], v0, s[4:5]
	s_add_u32 s4, s4, s13
	s_addc_u32 s5, s5, 0
	s_nop 0
	global_load_dwordx4 v[16:19], v0, s[4:5]
	s_add_u32 s4, s4, s13
	s_addc_u32 s5, s5, 0
	s_nop 0
	global_load_dwordx4 v[20:23], v0, s[4:5]
	s_add_u32 s4, s4, s13
	s_addc_u32 s5, s5, 0
	s_nop 0
	global_load_dwordx4 v[24:27], v0, s[4:5]
	s_add_u32 s4, s4, s13
	s_addc_u32 s5, s5, 0
	s_nop 0
	global_load_dwordx4 v[28:31], v0, s[4:5]
	s_add_u32 s4, s4, s13
	s_addc_u32 s5, s5, 0
	s_nop 0
	global_load_dwordx4 v[34:37], v0, s[4:5]
	s_add_u32 s4, s4, s13
	s_addc_u32 s5, s5, 0
	s_nop 0
	global_load_dwordx4 v[38:41], v0, s[4:5]
	s_mov_b32 s16, s6
	s_mov_b32 s17, s7
	s_mov_b32 s18, s2
	s_mov_b32 s19, s9
	s_add_i32 s0, s0, s1
	s_mov_b32 s24, 0
	s_cmp_ge_u32 s0, s14
	s_cbranch_scc1 .Lcvth_procA
	s_mov_b32 s23, 1
	s_mov_b32 s24, 1
	s_branch .Lcvth_dec
.Lcvth_ldB:
	v_mad_u32_u24 v106, v100, s8, v105
	s_lshl_b32 s13, s8, 3
	global_load_dwordx4 v[108:111], v106, s[4:5]
	s_add_u32 s4, s4, s13
	s_addc_u32 s5, s5, 0
	s_nop 0
	global_load_dwordx4 v[112:115], v106, s[4:5]
	s_add_u32 s4, s4, s13
	s_addc_u32 s5, s5, 0
	s_nop 0
	global_load_dwordx4 v[116:119], v106, s[4:5]
	s_add_u32 s4, s4, s13
	s_addc_u32 s5, s5, 0
	s_nop 0
	global_load_dwordx4 v[120:123], v106, s[4:5]
	s_add_u32 s4, s4, s13
	s_addc_u32 s5, s5, 0
	s_nop 0
	global_load_dwordx4 v[124:127], v106, s[4:5]
	s_add_u32 s4, s4, s13
	s_addc_u32 s5, s5, 0
	s_nop 0
	global_load_dwordx4 v[128:131], v106, s[4:5]
	s_add_u32 s4, s4, s13
	s_addc_u32 s5, s5, 0
	s_nop 0
	global_load_dwordx4 v[132:135], v106, s[4:5]
	s_add_u32 s4, s4, s13
	s_addc_u32 s5, s5, 0
	s_nop 0
	global_load_dwordx4 v[136:139], v106, s[4:5]
.Lcvth_procA:
	v_mov_b32_e32 v1, v104
	s_lshl_b32 s3, s19, 2
	s_mov_b32 s11, s3
	s_mov_b32 s13, s3
	s_cmp_eq_u32 s18, 0
	s_cbranch_scc0 .Lcvth_k0nA
	v_mov_b32_e32 v1, v100
	s_lshl_b32 s3, s19, 3
	s_mov_b32 s11, s3
	s_mov_b32 s13, s3
.Lcvth_k0nA:
	s_cmp_eq_u32 s18, 2
	s_cbranch_scc0 .Lcvth_k2nA
	v_mov_b32_e32 v1, v100
	s_lshl_b32 s3, s19, 3
	s_mul_i32 s11, s19, 24
	s_mov_b32 s13, s3
.Lcvth_k2nA:
	v_mul_u32_u24_e32 v1, s19, v1
	v_add_u32_e32 v1, v105, v1
	s_cmp_eq_u32 s24, 0
	s_cbranch_scc1 .Lcvth_wA0
	s_waitcnt vmcnt(8)
	s_branch .Lcvth_wAd

.Lcvth_wAd:
	ds_write_b32 v102, v8
	ds_write_b32 v102, v9 offset:4
	ds_write_b32 v102, v10 offset:8
	ds_write_b32 v102, v11 offset:12
	ds_write_b32 v102, v12 offset:1056
	ds_write_b32 v102, v13 offset:1060
	ds_write_b32 v102, v14 offset:1064
	ds_write_b32 v102, v15 offset:1068
	ds_write_b32 v102, v16 offset:2112
	ds_write_b32 v102, v17 offset:2116
	ds_write_b32 v102, v18 offset:2120
	ds_write_b32 v102, v19 offset:2124
	ds_write_b32 v102, v20 offset:3168
	ds_write_b32 v102, v21 offset:3172
	ds_write_b32 v102, v22 offset:3176
	ds_write_b32 v102, v23 offset:3180
	ds_write_b32 v102, v24 offset:4224
	ds_write_b32 v102, v25 offset:4228
	ds_write_b32 v102, v26 offset:4232
	ds_write_b32 v102, v27 offset:4236
	ds_write_b32 v102, v28 offset:5280
	ds_write_b32 v102, v29 offset:5284
	ds_write_b32 v102, v30 offset:5288
	ds_write_b32 v102, v31 offset:5292
	ds_write_b32 v102, v34 offset:6336
	ds_write_b32 v102, v35 offset:6340
	ds_write_b32 v102, v36 offset:6344
	ds_write_b32 v102, v37 offset:6348
	ds_write_b32 v102, v38 offset:7392
	ds_write_b32 v102, v39 offset:7396
	ds_write_b32 v102, v40 offset:7400
	ds_write_b32 v102, v41 offset:7404
	s_waitcnt lgkmcnt(0)
	ds_read2_b32 v[42:43], v103 offset0:0 offset1:33
	ds_read2_b32 v[44:45], v103 offset0:66 offset1:99
	ds_read2_b32 v[46:47], v103 offset0:132 offset1:165
	ds_read2_b32 v[48:49], v103 offset0:198 offset1:231
	ds_read2_b32 v[50:51], v103 offset0:8 offset1:41
	ds_read2_b32 v[52:53], v103 offset0:74 offset1:107
	ds_read2_b32 v[54:55], v103 offset0:140 offset1:173
	ds_read2_b32 v[56:57], v103 offset0:206 offset1:239
	ds_read2_b32 v[58:59], v103 offset0:16 offset1:49
	ds_read2_b32 v[60:61], v103 offset0:82 offset1:115
	ds_read2_b32 v[62:63], v103 offset0:148 offset1:181
	ds_read2_b32 v[64:65], v103 offset0:214 offset1:247
	ds_read2_b32 v[66:67], v103 offset0:24 offset1:57
	ds_read2_b32 v[68:69], v103 offset0:90 offset1:123
	ds_read2_b32 v[70:71], v103 offset0:156 offset1:189
	ds_read2_b32 v[72:73], v103 offset0:222 offset1:255
	s_waitcnt lgkmcnt(0)
	v_cvt_pk_f16_f32 v74, v42, v43
	v_cvt_pk_f16_f32 v75, v44, v45
	v_cvt_pk_f16_f32 v76, v46, v47
	v_cvt_pk_f16_f32 v77, v48, v49
	v_cvt_pk_f16_f32 v78, v50, v51
	v_cvt_pk_f16_f32 v79, v52, v53
	v_cvt_pk_f16_f32 v80, v54, v55
	v_cvt_pk_f16_f32 v81, v56, v57
	v_cvt_pk_f16_f32 v82, v58, v59
	v_cvt_pk_f16_f32 v83, v60, v61
	v_cvt_pk_f16_f32 v84, v62, v63
	v_cvt_pk_f16_f32 v85, v64, v65
	v_cvt_pk_f16_f32 v86, v66, v67
	v_cvt_pk_f16_f32 v87, v68, v69
	v_cvt_pk_f16_f32 v88, v70, v71
	v_cvt_pk_f16_f32 v89, v72, v73
	global_store_dwordx4 v1, v[74:77], s[16:17]
	s_add_u32 s16, s16, s3
	s_addc_u32 s17, s17, 0
	s_nop 0
	global_store_dwordx4 v1, v[78:81], s[16:17]
	s_add_u32 s16, s16, s11
	s_addc_u32 s17, s17, 0
	s_nop 0
	global_store_dwordx4 v1, v[82:85], s[16:17]
	s_add_u32 s16, s16, s13
	s_addc_u32 s17, s17, 0
	s_nop 0
	global_store_dwordx4 v1, v[86:89], s[16:17]
	s_cmp_eq_u32 s24, 0
	s_cbranch_scc1 .Lcvth_loop
	v_mov_b32_e32 v1, v104
	s_lshl_b32 s3, s9, 2
	s_mov_b32 s11, s3
	s_mov_b32 s13, s3
	s_cmp_eq_u32 s2, 0
	s_cbranch_scc0 .Lcvth_k0nB
	v_mov_b32_e32 v1, v100
	s_lshl_b32 s3, s9, 3
	s_mov_b32 s11, s3
	s_mov_b32 s13, s3

.Lcvth_k2nB:
	v_mul_u32_u24_e32 v1, s9, v1
	v_add_u32_e32 v1, v105, v1
	s_waitcnt vmcnt(4)
	ds_write_b32 v102, v108
	ds_write_b32 v102, v109 offset:4
	ds_write_b32 v102, v110 offset:8
	ds_write_b32 v102, v111 offset:12
	ds_write_b32 v102, v112 offset:1056
	ds_write_b32 v102, v113 offset:1060
	ds_write_b32 v102, v114 offset:1064
	ds_write_b32 v102, v115 offset:1068
	ds_write_b32 v102, v116 offset:2112
	ds_write_b32 v102, v117 offset:2116
	ds_write_b32 v102, v118 offset:2120
	ds_write_b32 v102, v119 offset:2124
	ds_write_b32 v102, v120 offset:3168
	ds_write_b32 v102, v121 offset:3172
	ds_write_b32 v102, v122 offset:3176
	ds_write_b32 v102, v123 offset:3180
	ds_write_b32 v102, v124 offset:4224
	ds_write_b32 v102, v125 offset:4228
	ds_write_b32 v102, v126 offset:4232
	ds_write_b32 v102, v127 offset:4236
	ds_write_b32 v102, v128 offset:5280
	ds_write_b32 v102, v129 offset:5284
	ds_write_b32 v102, v130 offset:5288
	ds_write_b32 v102, v131 offset:5292
	ds_write_b32 v102, v132 offset:6336
	ds_write_b32 v102, v133 offset:6340
	ds_write_b32 v102, v134 offset:6344
	ds_write_b32 v102, v135 offset:6348
	ds_write_b32 v102, v136 offset:7392
	ds_write_b32 v102, v137 offset:7396
	ds_write_b32 v102, v138 offset:7400
	ds_write_b32 v102, v139 offset:7404
	s_waitcnt lgkmcnt(0)
	ds_read2_b32 v[42:43], v103 offset0:0 offset1:33
	ds_read2_b32 v[44:45], v103 offset0:66 offset1:99
	ds_read2_b32 v[46:47], v103 offset0:132 offset1:165
	ds_read2_b32 v[48:49], v103 offset0:198 offset1:231
	ds_read2_b32 v[50:51], v103 offset0:8 offset1:41
	ds_read2_b32 v[52:53], v103 offset0:74 offset1:107
	ds_read2_b32 v[54:55], v103 offset0:140 offset1:173
	ds_read2_b32 v[56:57], v103 offset0:206 offset1:239
	ds_read2_b32 v[58:59], v103 offset0:16 offset1:49
	ds_read2_b32 v[60:61], v103 offset0:82 offset1:115
	ds_read2_b32 v[62:63], v103 offset0:148 offset1:181
	ds_read2_b32 v[64:65], v103 offset0:214 offset1:247
	ds_read2_b32 v[66:67], v103 offset0:24 offset1:57
	ds_read2_b32 v[68:69], v103 offset0:90 offset1:123
	ds_read2_b32 v[70:71], v103 offset0:156 offset1:189
	ds_read2_b32 v[72:73], v103 offset0:222 offset1:255
	s_waitcnt lgkmcnt(0)
	v_cvt_pk_f16_f32 v74, v42, v43
	v_cvt_pk_f16_f32 v75, v44, v45
	v_cvt_pk_f16_f32 v76, v46, v47
	v_cvt_pk_f16_f32 v77, v48, v49
	v_cvt_pk_f16_f32 v78, v50, v51
	v_cvt_pk_f16_f32 v79, v52, v53
	v_cvt_pk_f16_f32 v80, v54, v55
	v_cvt_pk_f16_f32 v81, v56, v57
	v_cvt_pk_f16_f32 v82, v58, v59
	v_cvt_pk_f16_f32 v83, v60, v61
	v_cvt_pk_f16_f32 v84, v62, v63
	v_cvt_pk_f16_f32 v85, v64, v65
	v_cvt_pk_f16_f32 v86, v66, v67
	v_cvt_pk_f16_f32 v87, v68, v69
	v_cvt_pk_f16_f32 v88, v70, v71
	v_cvt_pk_f16_f32 v89, v72, v73
	global_store_dwordx4 v1, v[74:77], s[6:7]
	s_add_u32 s6, s6, s3
	s_addc_u32 s7, s7, 0
	s_nop 0
	global_store_dwordx4 v1, v[78:81], s[6:7]
	s_add_u32 s6, s6, s11
	s_addc_u32 s7, s7, 0
	s_nop 0
	global_store_dwordx4 v1, v[82:85], s[6:7]
	s_add_u32 s6, s6, s13
	s_addc_u32 s7, s7, 0
	s_nop 0
	global_store_dwordx4 v1, v[86:89], s[6:7]
	s_add_i32 s0, s0, s1
	s_branch .Lcvth_loop
